# hot loop headers (5 GEMM K-loops, 2 attention loops) aligned to 64 B
# speedup vs baseline: 1.0011x; 1.0011x over previous
; template <class Epi, class Sched, bool ALIGN_EPI = false, bool SP2 = false, bool SPLITK = false>
; __device__ __forceinline__ void gemm_phase(PG8_LAS unsigned char* lds, const Gemm g, const Sched& S, const Epi& E) {
;     ...
;         const bool has_next = S.next(ui + 1, nxt);
;         const char* nA = has_next ? (const char*)g.A + (size_t)nxt.pm * tstep : cA; const char* nB = has_next ? (const char*)g.Bt + (size_t)nxt.pn * tstep : cB;
;     ...
; #pragma unroll
;         for (int a = 0; a < 2; ++a)
; #pragma unroll
;             for (int b = 0; b < 2; ++b)
; #pragma unroll
;                 for (int m = 0; m < 4; ++m)
; #pragma unroll
;                     for (int n = 0; n < 2; ++n) acc[a][b][m][n] = (f32x4){0.f, 0.f, 0.f, 0.f};
.LBB0_164:
	s_ashr_i32 s35, s34, 31
	s_lshl_b64 s[22:23], s[34:35], 19
	s_add_u32 s36, s82, s22
	s_addc_u32 s37, s83, s23
	s_and_b64 s[22:23], s[38:39], exec
	s_cselect_b32 s4, s37, s49
	s_cselect_b32 s12, s36, s48
	s_ashr_i32 s21, s20, 31
	s_lshl_b64 s[22:23], s[20:21], 19
	v_readlane_b32 s21, v255, 45
	s_add_u32 s40, s21, s22
	v_readlane_b32 s21, v255, 46
	s_addc_u32 s41, s21, s23
	s_and_b64 s[22:23], s[38:39], exec
	s_cselect_b32 s21, s41, s47
	s_cselect_b32 s22, s40, s46
	s_add_u32 s54, s48, 0x40080
	s_addc_u32 s55, s49, 0
	s_add_u32 s23, s46, 0x100
	v_mov_b32_e32 v2, 0
	s_addc_u32 s24, s47, 0
	s_mov_b32 s25, -2
	v_mov_b32_e32 v3, v2
	v_mov_b32_e32 v4, v2
	v_mov_b32_e32 v5, v2
	v_mov_b32_e32 v6, v2
	v_mov_b32_e32 v7, v2
	v_mov_b32_e32 v8, v2
	v_mov_b32_e32 v9, v2
	v_mov_b32_e32 v14, v2
	v_mov_b32_e32 v15, v2
	v_mov_b32_e32 v16, v2
	v_mov_b32_e32 v17, v2
	v_mov_b32_e32 v22, v2
	v_mov_b32_e32 v23, v2
	v_mov_b32_e32 v24, v2
	v_mov_b32_e32 v25, v2
	v_mov_b32_e32 v30, v2
	v_mov_b32_e32 v31, v2
	v_mov_b32_e32 v32, v2
	v_mov_b32_e32 v33, v2
	v_mov_b32_e32 v38, v2
	v_mov_b32_e32 v39, v2
	v_mov_b32_e32 v40, v2
	v_mov_b32_e32 v41, v2
	v_mov_b32_e32 v46, v2
	v_mov_b32_e32 v47, v2
	v_mov_b32_e32 v48, v2
	v_mov_b32_e32 v49, v2
	v_mov_b32_e32 v54, v2
	v_mov_b32_e32 v55, v2
	v_mov_b32_e32 v56, v2
	v_mov_b32_e32 v57, v2
	v_mov_b32_e32 v10, v2
	v_mov_b32_e32 v11, v2
	v_mov_b32_e32 v12, v2
	v_mov_b32_e32 v13, v2
	v_mov_b32_e32 v18, v2
	v_mov_b32_e32 v19, v2
	v_mov_b32_e32 v20, v2
	v_mov_b32_e32 v21, v2
	v_mov_b32_e32 v26, v2
	v_mov_b32_e32 v27, v2
	v_mov_b32_e32 v28, v2
	v_mov_b32_e32 v29, v2
	v_mov_b32_e32 v34, v2
	v_mov_b32_e32 v35, v2
	v_mov_b32_e32 v36, v2
	v_mov_b32_e32 v37, v2
	v_mov_b32_e32 v42, v2
	v_mov_b32_e32 v43, v2
	v_mov_b32_e32 v44, v2
	v_mov_b32_e32 v45, v2
	v_mov_b32_e32 v50, v2
	v_mov_b32_e32 v51, v2
	v_mov_b32_e32 v52, v2
	v_mov_b32_e32 v53, v2
	v_mov_b32_e32 v58, v2
	v_mov_b32_e32 v59, v2
	v_mov_b32_e32 v60, v2
	v_mov_b32_e32 v61, v2
	v_mov_b32_e32 v62, v2
	v_mov_b32_e32 v63, v2
	v_mov_b32_e32 v64, v2
	v_mov_b32_e32 v65, v2
	v_mov_b32_e32 v66, v2
	v_mov_b32_e32 v67, v2
	v_mov_b32_e32 v68, v2
	v_mov_b32_e32 v69, v2
	v_mov_b32_e32 v70, v2
	v_mov_b32_e32 v71, v2
	v_mov_b32_e32 v72, v2
	v_mov_b32_e32 v73, v2
	v_mov_b32_e32 v78, v2
	v_mov_b32_e32 v79, v2
	v_mov_b32_e32 v80, v2
	v_mov_b32_e32 v81, v2
	v_mov_b32_e32 v86, v2
	v_mov_b32_e32 v87, v2
	v_mov_b32_e32 v88, v2
	v_mov_b32_e32 v89, v2
	v_mov_b32_e32 v94, v2
	v_mov_b32_e32 v95, v2
	v_mov_b32_e32 v96, v2
	v_mov_b32_e32 v97, v2
	v_mov_b32_e32 v102, v2
	v_mov_b32_e32 v103, v2
	v_mov_b32_e32 v104, v2
	v_mov_b32_e32 v105, v2
	v_mov_b32_e32 v110, v2
	v_mov_b32_e32 v111, v2
	v_mov_b32_e32 v112, v2
	v_mov_b32_e32 v113, v2
	v_mov_b32_e32 v118, v2
	v_mov_b32_e32 v119, v2
	v_mov_b32_e32 v120, v2
	v_mov_b32_e32 v121, v2
	v_mov_b32_e32 v74, v2
	v_mov_b32_e32 v75, v2
	v_mov_b32_e32 v76, v2
	v_mov_b32_e32 v77, v2
	v_mov_b32_e32 v82, v2
	v_mov_b32_e32 v83, v2
	v_mov_b32_e32 v84, v2
	v_mov_b32_e32 v85, v2
	v_mov_b32_e32 v90, v2
	v_mov_b32_e32 v91, v2
	v_mov_b32_e32 v92, v2
	v_mov_b32_e32 v93, v2
	v_mov_b32_e32 v98, v2
	v_mov_b32_e32 v99, v2
	v_mov_b32_e32 v100, v2
	v_mov_b32_e32 v101, v2
	v_mov_b32_e32 v106, v2
	v_mov_b32_e32 v107, v2
	v_mov_b32_e32 v108, v2
	v_mov_b32_e32 v109, v2
	v_mov_b32_e32 v114, v2
	v_mov_b32_e32 v115, v2
	v_mov_b32_e32 v116, v2
	v_mov_b32_e32 v117, v2
	v_mov_b32_e32 v122, v2
	v_mov_b32_e32 v123, v2
	v_mov_b32_e32 v124, v2
	v_mov_b32_e32 v125, v2
	v_mov_b32_e32 v126, v2
	v_mov_b32_e32 v127, v2
	v_mov_b32_e32 v128, v2
	v_mov_b32_e32 v129, v2
	.p2align	6

; #define WAIT_BAR(N) asm volatile("s_waitcnt vmcnt(" #N ") lgkmcnt(0)\n\ts_barrier":::"memory")
;   #define DMA_K(t,slot) glds16(ksrc+(long)(t)*KVBLK*DM,(unsigned)__builtin_amdgcn_readfirstlane(kdst+(slot)))
;   #define DMA_V(t,slot) do{ glds16(vsrc+(long)(t)*KVBLK*DM,(unsigned)__builtin_amdgcn_readfirstlane(vdst+2*(slot))); glds16(vsrc+(long)(t)*KVBLK*DM+64,(unsigned)__builtin_amdgcn_readfirstlane(vdst+2*(slot)+8192)); }while(0)
;   #define ROT() do{sl_prev=sl_cur;sl_cur=sl_next;sl_next=(sl_next==(NSLOT-1)*SLOTB)?0:sl_next+SLOTB;}while(0)
; template<int THRL> __device__ __forceinline__ void attn_unit(int b,int hq,int vcol,int qb,const bf16*Q,const bf16*__restrict__ K,const bf16*__restrict__ V,bf16*O,char*shm){
;     ...
;   _Pragma("unroll") for(int r=0;r<16;++r)pA1[r]=__builtin_amdgcn_exp2f(pA1[r]);
;   WAIT_BAR(0);
;   DMA_K(3,0);DMA_V(1,SLOTB);
;   ROT();
;   kload8(kf,kp0+sl_cur);
;     ...
;   if(wid>=4)__builtin_amdgcn_s_setprio(1);
;   int t=1;
;     ...
;   for(;t+5<NT;t+=2){
.LBB0_262:
	v_exp_f32_e32 v96, v0
	v_lshlrev_b32_e32 v0, 1, v36
	s_and_b32 s2, s33, 0x3fffffc0
	v_and_b32_e32 v226, 32, v0
	v_lshlrev_b32_e32 v0, 4, v36
	v_exp_f32_e32 v112, v18
	v_exp_f32_e32 v113, v19
	v_exp_f32_e32 v114, v20
	v_exp_f32_e32 v115, v21
	v_exp_f32_e32 v116, v22
	v_exp_f32_e32 v117, v23
	v_exp_f32_e32 v118, v24
	v_exp_f32_e32 v119, v25
	v_exp_f32_e32 v120, v26
	v_exp_f32_e32 v121, v27
	v_exp_f32_e32 v122, v28
	v_exp_f32_e32 v123, v29
	v_exp_f32_e32 v124, v30
	v_exp_f32_e32 v125, v31
	v_exp_f32_e32 v126, v32
	v_exp_f32_e32 v127, v33
	v_exp_f32_e32 v97, v2
	v_exp_f32_e32 v98, v3
	v_exp_f32_e32 v99, v4
	v_exp_f32_e32 v100, v5
	v_exp_f32_e32 v101, v6
	v_exp_f32_e32 v102, v7
	v_exp_f32_e32 v103, v8
	v_exp_f32_e32 v104, v9
	v_exp_f32_e32 v105, v10
	v_exp_f32_e32 v106, v11
	v_exp_f32_e32 v107, v12
	v_exp_f32_e32 v108, v13
	v_exp_f32_e32 v109, v14
	v_exp_f32_e32 v110, v15
	v_exp_f32_e32 v111, v16
	v_and_b32_e32 v0, 0xc0, v0
	s_lshl_b32 s2, s2, 2
	v_lshl_or_b32 v225, v252, 8, v0
	v_add_u32_e32 v0, 0, v226
	s_add_i32 s88, s2, 0
	s_add_i32 s88, s88, 0x12000
	v_add3_u32 v233, v0, v247, v225
	v_and_b32_e32 v0, 3, v36
	s_mov_b32 s90, 1
	s_andn2_b64 vcc, exec, s[52:53]
	v_cmp_gt_u32_e64 s[38:39], 32, v250
	v_lshlrev_b32_e32 v234, 4, v252
	v_lshl_add_u32 v224, v251, 2, s88
	v_lshlrev_b32_e32 v240, 4, v0
	s_cbranch_vccnz .LBB0_278
	s_lshl_b32 s2, s33, 9
	v_mov_b32_e32 v241, v1
	s_and_b32 s2, s2, 0x18000
	v_lshl_add_u64 v[2:3], s[92:93], 1, v[240:241]
	v_lshl_or_b32 v0, v228, 11, s2
	v_lshl_add_u64 v[2:3], v[2:3], 0, v[0:1]
	v_mov_b32_e32 v14, v1
	v_mov_b32_e32 v15, v1
	v_lshl_add_u64 v[242:243], s[20:21], 0, v[2:3]
	v_mov_b32_e32 v0, v1
	v_mov_b32_e32 v2, v1
	v_mov_b32_e32 v3, v1
	v_mov_b32_e32 v4, v1
	v_mov_b32_e32 v5, v1
	v_mov_b32_e32 v6, v1
	v_mov_b32_e32 v7, v1
	v_mov_b32_e32 v8, v1
	v_mov_b32_e32 v9, v1
	v_mov_b32_e32 v10, v1
	v_mov_b32_e32 v11, v1
	v_mov_b32_e32 v12, v1
	v_mov_b32_e32 v13, v1
	v_mov_b64_e32 v[78:79], v[14:15]
	v_mov_b64_e32 v[62:63], v[14:15]
	v_mov_b64_e32 v[46:47], v[14:15]
	v_mov_b64_e32 v[30:31], v[14:15]
	s_mov_b32 s2, 0
	s_movk_i32 s96, 0x4000
	s_movk_i32 s4, 0x2000
	v_mov_b32_e32 v235, 0
	s_mov_b32 s45, 6
	s_mov_b64 s[54:55], 0
	v_mov_b64_e32 v[76:77], v[12:13]
	v_mov_b64_e32 v[74:75], v[10:11]
	v_mov_b64_e32 v[72:73], v[8:9]
	v_mov_b64_e32 v[70:71], v[6:7]
	v_mov_b64_e32 v[68:69], v[4:5]
	v_mov_b64_e32 v[66:67], v[2:3]
	v_mov_b64_e32 v[64:65], v[0:1]
	v_mov_b64_e32 v[60:61], v[12:13]
	v_mov_b64_e32 v[58:59], v[10:11]
	v_mov_b64_e32 v[56:57], v[8:9]
	v_mov_b64_e32 v[54:55], v[6:7]
	v_mov_b64_e32 v[52:53], v[4:5]
	v_mov_b64_e32 v[50:51], v[2:3]
	v_mov_b64_e32 v[48:49], v[0:1]
	v_mov_b64_e32 v[44:45], v[12:13]
	v_mov_b64_e32 v[42:43], v[10:11]
	v_mov_b64_e32 v[40:41], v[8:9]
	v_mov_b64_e32 v[38:39], v[6:7]
	v_mov_b64_e32 v[36:37], v[4:5]
	v_mov_b64_e32 v[34:35], v[2:3]
	v_mov_b64_e32 v[32:33], v[0:1]
	v_mov_b64_e32 v[28:29], v[12:13]
	v_mov_b64_e32 v[26:27], v[10:11]
	v_mov_b64_e32 v[24:25], v[8:9]
	v_mov_b64_e32 v[22:23], v[6:7]
	v_mov_b64_e32 v[20:21], v[4:5]
	v_mov_b64_e32 v[18:19], v[2:3]
	v_mov_b64_e32 v[16:17], v[0:1]
	.p2align	6

;   #define RESC() do{ if(resc){ asm volatile("s_waitcnt lgkmcnt(0)":::"memory"); \
;       _Pragma("unroll") for(int d_=0;d_<4;++d_) _Pragma("unroll") for(int r=0;r<16;++r)o[d_][r]*=wsf[crow(r,hi)]; } }while(0)
;   #define ROT() do{sl_prev=sl_cur;sl_cur=sl_next;sl_next=(sl_next==(NSLOT-1)*SLOTB)?0:sl_next+SLOTB;}while(0)
;   #define ENDW(tt) do{ if((tt)+3<NT){WAIT_BAR(3);} else if((tt)+2<NT){WAIT_BAR(2);} else {WAIT_BAR(0);} }while(0)
; template<int THRL> __device__ __forceinline__ void attn_unit(int b,int hq,int vcol,int qb,const bf16*Q,const bf16*__restrict__ K,const bf16*__restrict__ V,bf16*O,char*shm){
;     ...
;   for(;t+1<NT;t+=2){
;     STEP(pB0,pB1,pA0,pA1,t,(t+3<NT),(t+1<NT),(t+1<NT));       ENDW(t);   RESC(); ROT();
.LBB0_283:
	s_andn2_b64 vcc, exec, s[38:39]
	s_cbranch_vccnz .LBB0_333
	s_lshl_b32 s2, s33, 9
	v_mov_b32_e32 v241, v1
	s_and_b32 s2, s2, 0x18000
	v_lshl_add_u64 v[2:3], s[92:93], 1, v[240:241]
	v_lshl_or_b32 v0, v228, 11, s2
	v_lshl_add_u64 v[2:3], v[2:3], 0, v[0:1]
	s_ashr_i32 s45, s33, 7
	v_cmp_gt_u32_e64 s[38:39], 32, v250
	s_add_i32 s12, s90, 2
	s_lshl_b64 s[94:95], s[90:91], 17
	v_lshl_add_u64 v[14:15], s[20:21], 0, v[2:3]
	.p2align	6

; template <class Epi, class Sched, bool ALIGN_EPI = false, bool SP2 = false, bool SPLITK = false>
; __device__ __forceinline__ void gemm_phase(PG8_LAS unsigned char* lds, const Gemm g, const Sched& S, const Epi& E) {
;     ...
;         for (int t = 0; t < nt; t += 2) {
;             const bool last = (t == nt - 2);
;             if constexpr (SPLITK) { if (t == nt1) E.mid(acc, cur, wr, wc, fr, fq); }
;             const char* a1 = PG8_TA(t + 1);
;             const char* a2 = last ? nA : PG8_TA(t + 2); const char* b2 = last ? nB : PG8_TB(t + 2);
;             const char* a3 = a2 + kstep; const char* b3 = b2 + kstep;
.LBB0_414:
	s_andn2_b64 vcc, exec, s[46:47]
	s_mov_b32 s46, s36
	s_mov_b32 s54, s40
	s_mov_b64 s[48:49], s[52:53]
	s_mov_b64 s[96:97], s[42:43]
	s_cbranch_vccz .LBB0_440
	.p2align	6

; template <class Epi, class Sched, bool ALIGN_EPI = false, bool SP2 = false, bool SPLITK = false>
; __device__ __forceinline__ void gemm_phase(PG8_LAS unsigned char* lds, const Gemm g, const Sched& S, const Epi& E) {
;     ...
;         const bool has_next = S.next(ui + 1, nxt);
;         const char* nA = has_next ? (const char*)g.A + (size_t)nxt.pm * tstep : cA; const char* nB = has_next ? (const char*)g.Bt + (size_t)nxt.pn * tstep : cB;
;     ...
; #pragma unroll
;         for (int a = 0; a < 2; ++a)
; #pragma unroll
;             for (int b = 0; b < 2; ++b)
; #pragma unroll
;                 for (int m = 0; m < 4; ++m)
; #pragma unroll
;                     for (int n = 0; n < 2; ++n) acc[a][b][m][n] = (f32x4){0.f, 0.f, 0.f, 0.f};
.LBB0_509:
	s_ashr_i32 s35, s34, 31
	s_lshl_b64 s[36:37], s[34:35], 19
	s_add_u32 s36, s14, s36
	s_addc_u32 s37, s15, s37
	s_and_b64 s[40:41], s[38:39], exec
	s_cselect_b32 s12, s37, s49
	s_cselect_b32 s19, s36, s48
	s_ashr_i32 s21, s20, 31
	s_lshl_b64 s[40:41], s[20:21], 19
	s_add_u32 s40, s22, s40
	s_addc_u32 s41, s23, s41
	s_and_b64 s[52:53], s[38:39], exec
	s_cselect_b32 s21, s41, s47
	s_cselect_b32 s35, s40, s46
	s_add_u32 s52, s48, 0x40080
	s_addc_u32 s53, s49, 0
	s_add_u32 s43, s46, 0x100
	v_mov_b32_e32 v2, 0
	s_addc_u32 s45, s47, 0
	s_mov_b32 s58, -2
	v_mov_b32_e32 v3, v2
	v_mov_b32_e32 v4, v2
	v_mov_b32_e32 v5, v2
	v_mov_b32_e32 v6, v2
	v_mov_b32_e32 v7, v2
	v_mov_b32_e32 v8, v2
	v_mov_b32_e32 v9, v2
	v_mov_b32_e32 v18, v2
	v_mov_b32_e32 v19, v2
	v_mov_b32_e32 v20, v2
	v_mov_b32_e32 v21, v2
	v_mov_b32_e32 v22, v2
	v_mov_b32_e32 v23, v2
	v_mov_b32_e32 v24, v2
	v_mov_b32_e32 v25, v2
	v_mov_b32_e32 v34, v2
	v_mov_b32_e32 v35, v2
	v_mov_b32_e32 v36, v2
	v_mov_b32_e32 v37, v2
	v_mov_b32_e32 v38, v2
	v_mov_b32_e32 v39, v2
	v_mov_b32_e32 v40, v2
	v_mov_b32_e32 v41, v2
	v_mov_b32_e32 v50, v2
	v_mov_b32_e32 v51, v2
	v_mov_b32_e32 v52, v2
	v_mov_b32_e32 v53, v2
	v_mov_b32_e32 v54, v2
	v_mov_b32_e32 v55, v2
	v_mov_b32_e32 v56, v2
	v_mov_b32_e32 v57, v2
	v_mov_b32_e32 v10, v2
	v_mov_b32_e32 v11, v2
	v_mov_b32_e32 v12, v2
	v_mov_b32_e32 v13, v2
	v_mov_b32_e32 v14, v2
	v_mov_b32_e32 v15, v2
	v_mov_b32_e32 v16, v2
	v_mov_b32_e32 v17, v2
	v_mov_b32_e32 v26, v2
	v_mov_b32_e32 v27, v2
	v_mov_b32_e32 v28, v2
	v_mov_b32_e32 v29, v2
	v_mov_b32_e32 v30, v2
	v_mov_b32_e32 v31, v2
	v_mov_b32_e32 v32, v2
	v_mov_b32_e32 v33, v2
	v_mov_b32_e32 v42, v2
	v_mov_b32_e32 v43, v2
	v_mov_b32_e32 v44, v2
	v_mov_b32_e32 v45, v2
	v_mov_b32_e32 v46, v2
	v_mov_b32_e32 v47, v2
	v_mov_b32_e32 v48, v2
	v_mov_b32_e32 v49, v2
	v_mov_b32_e32 v58, v2
	v_mov_b32_e32 v59, v2
	v_mov_b32_e32 v60, v2
	v_mov_b32_e32 v61, v2
	v_mov_b32_e32 v62, v2
	v_mov_b32_e32 v63, v2
	v_mov_b32_e32 v64, v2
	v_mov_b32_e32 v65, v2
	v_mov_b32_e32 v66, v2
	v_mov_b32_e32 v67, v2
	v_mov_b32_e32 v68, v2
	v_mov_b32_e32 v69, v2
	v_mov_b32_e32 v70, v2
	v_mov_b32_e32 v71, v2
	v_mov_b32_e32 v72, v2
	v_mov_b32_e32 v73, v2
	v_mov_b32_e32 v86, v2
	v_mov_b32_e32 v87, v2
	v_mov_b32_e32 v88, v2
	v_mov_b32_e32 v89, v2
	v_mov_b32_e32 v90, v2
	v_mov_b32_e32 v91, v2
	v_mov_b32_e32 v92, v2
	v_mov_b32_e32 v93, v2
	v_mov_b32_e32 v110, v2
	v_mov_b32_e32 v111, v2
	v_mov_b32_e32 v112, v2
	v_mov_b32_e32 v113, v2
	v_mov_b32_e32 v114, v2
	v_mov_b32_e32 v115, v2
	v_mov_b32_e32 v116, v2
	v_mov_b32_e32 v117, v2
	v_mov_b32_e32 v134, v2
	v_mov_b32_e32 v135, v2
	v_mov_b32_e32 v136, v2
	v_mov_b32_e32 v137, v2
	v_mov_b32_e32 v138, v2
	v_mov_b32_e32 v139, v2
	v_mov_b32_e32 v140, v2
	v_mov_b32_e32 v141, v2
	v_mov_b32_e32 v74, v2
	v_mov_b32_e32 v75, v2
	v_mov_b32_e32 v76, v2
	v_mov_b32_e32 v77, v2
	v_mov_b32_e32 v78, v2
	v_mov_b32_e32 v79, v2
	v_mov_b32_e32 v80, v2
	v_mov_b32_e32 v81, v2
	v_mov_b32_e32 v98, v2
	v_mov_b32_e32 v99, v2
	v_mov_b32_e32 v100, v2
	v_mov_b32_e32 v101, v2
	v_mov_b32_e32 v102, v2
	v_mov_b32_e32 v103, v2
	v_mov_b32_e32 v104, v2
	v_mov_b32_e32 v105, v2
	v_mov_b32_e32 v122, v2
	v_mov_b32_e32 v123, v2
	v_mov_b32_e32 v124, v2
	v_mov_b32_e32 v125, v2
	v_mov_b32_e32 v126, v2
	v_mov_b32_e32 v127, v2
	v_mov_b32_e32 v128, v2
	v_mov_b32_e32 v129, v2
	v_mov_b32_e32 v154, v2
	v_mov_b32_e32 v155, v2
	v_mov_b32_e32 v156, v2
	v_mov_b32_e32 v157, v2
	v_mov_b32_e32 v158, v2
	v_mov_b32_e32 v159, v2
	v_mov_b32_e32 v160, v2
	v_mov_b32_e32 v161, v2
	.p2align	6

; template <class Epi, class Sched, bool ALIGN_EPI = false, bool SP2 = false, bool SPLITK = false>
; __device__ __forceinline__ void gemm_phase(PG8_LAS unsigned char* lds, const Gemm g, const Sched& S, const Epi& E) {
;     ...
;         const bool has_next = S.next(ui + 1, nxt);
;         const char* nA = has_next ? (const char*)g.A + (size_t)nxt.pm * tstep : cA; const char* nB = has_next ? (const char*)g.Bt + (size_t)nxt.pn * tstep : cB;
;     ...
; #pragma unroll
;         for (int a = 0; a < 2; ++a)
; #pragma unroll
;             for (int b = 0; b < 2; ++b)
; #pragma unroll
;                 for (int m = 0; m < 4; ++m)
; #pragma unroll
;                     for (int n = 0; n < 2; ++n) acc[a][b][m][n] = (f32x4){0.f, 0.f, 0.f, 0.f};
.LBB0_581:
	s_ashr_i32 s21, s20, 31
	s_lshl_b64 s[34:35], s[20:21], 19
	s_add_u32 s34, s82, s34
	s_addc_u32 s35, s83, s35
	s_and_b64 s[36:37], s[38:39], exec
	s_cselect_b32 s4, s35, s43
	s_cselect_b32 s12, s34, s42
	s_ashr_i32 s19, s18, 31
	s_lshl_b64 s[36:37], s[18:19], 19
	s_add_u32 s36, s33, s36
	s_addc_u32 s37, s50, s37
	s_and_b64 s[48:49], s[38:39], exec
	s_cselect_b32 s19, s37, s47
	s_cselect_b32 s21, s36, s46
	s_add_u32 s42, s42, 0x40080
	s_addc_u32 s43, s43, 0
	s_add_u32 s25, s46, 0x100
	v_mov_b32_e32 v2, 0
	s_addc_u32 s41, s47, 0
	s_mov_b32 s45, -2
	v_mov_b32_e32 v3, v2
	v_mov_b32_e32 v4, v2
	v_mov_b32_e32 v5, v2
	v_mov_b32_e32 v10, v2
	v_mov_b32_e32 v11, v2
	v_mov_b32_e32 v12, v2
	v_mov_b32_e32 v13, v2
	v_mov_b32_e32 v18, v2
	v_mov_b32_e32 v19, v2
	v_mov_b32_e32 v20, v2
	v_mov_b32_e32 v21, v2
	v_mov_b32_e32 v26, v2
	v_mov_b32_e32 v27, v2
	v_mov_b32_e32 v28, v2
	v_mov_b32_e32 v29, v2
	v_mov_b32_e32 v34, v2
	v_mov_b32_e32 v35, v2
	v_mov_b32_e32 v36, v2
	v_mov_b32_e32 v37, v2
	v_mov_b32_e32 v42, v2
	v_mov_b32_e32 v43, v2
	v_mov_b32_e32 v44, v2
	v_mov_b32_e32 v45, v2
	v_mov_b32_e32 v50, v2
	v_mov_b32_e32 v51, v2
	v_mov_b32_e32 v52, v2
	v_mov_b32_e32 v53, v2
	v_mov_b32_e32 v58, v2
	v_mov_b32_e32 v59, v2
	v_mov_b32_e32 v60, v2
	v_mov_b32_e32 v61, v2
	v_mov_b32_e32 v6, v2
	v_mov_b32_e32 v7, v2
	v_mov_b32_e32 v8, v2
	v_mov_b32_e32 v9, v2
	v_mov_b32_e32 v14, v2
	v_mov_b32_e32 v15, v2
	v_mov_b32_e32 v16, v2
	v_mov_b32_e32 v17, v2
	v_mov_b32_e32 v22, v2
	v_mov_b32_e32 v23, v2
	v_mov_b32_e32 v24, v2
	v_mov_b32_e32 v25, v2
	v_mov_b32_e32 v30, v2
	v_mov_b32_e32 v31, v2
	v_mov_b32_e32 v32, v2
	v_mov_b32_e32 v33, v2
	v_mov_b32_e32 v38, v2
	v_mov_b32_e32 v39, v2
	v_mov_b32_e32 v40, v2
	v_mov_b32_e32 v41, v2
	v_mov_b32_e32 v46, v2
	v_mov_b32_e32 v47, v2
	v_mov_b32_e32 v48, v2
	v_mov_b32_e32 v49, v2
	v_mov_b32_e32 v54, v2
	v_mov_b32_e32 v55, v2
	v_mov_b32_e32 v56, v2
	v_mov_b32_e32 v57, v2
	v_mov_b32_e32 v62, v2
	v_mov_b32_e32 v63, v2
	v_mov_b32_e32 v64, v2
	v_mov_b32_e32 v65, v2
	v_mov_b32_e32 v66, v2
	v_mov_b32_e32 v67, v2
	v_mov_b32_e32 v68, v2
	v_mov_b32_e32 v69, v2
	v_mov_b32_e32 v74, v2
	v_mov_b32_e32 v75, v2
	v_mov_b32_e32 v76, v2
	v_mov_b32_e32 v77, v2
	v_mov_b32_e32 v82, v2
	v_mov_b32_e32 v83, v2
	v_mov_b32_e32 v84, v2
	v_mov_b32_e32 v85, v2
	v_mov_b32_e32 v90, v2
	v_mov_b32_e32 v91, v2
	v_mov_b32_e32 v92, v2
	v_mov_b32_e32 v93, v2
	v_mov_b32_e32 v98, v2
	v_mov_b32_e32 v99, v2
	v_mov_b32_e32 v100, v2
	v_mov_b32_e32 v101, v2
	v_mov_b32_e32 v106, v2
	v_mov_b32_e32 v107, v2
	v_mov_b32_e32 v108, v2
	v_mov_b32_e32 v109, v2
	v_mov_b32_e32 v114, v2
	v_mov_b32_e32 v115, v2
	v_mov_b32_e32 v116, v2
	v_mov_b32_e32 v117, v2
	v_mov_b32_e32 v122, v2
	v_mov_b32_e32 v123, v2
	v_mov_b32_e32 v124, v2
	v_mov_b32_e32 v125, v2
	v_mov_b32_e32 v70, v2
	v_mov_b32_e32 v71, v2
	v_mov_b32_e32 v72, v2
	v_mov_b32_e32 v73, v2
	v_mov_b32_e32 v78, v2
	v_mov_b32_e32 v79, v2
	v_mov_b32_e32 v80, v2
	v_mov_b32_e32 v81, v2
	v_mov_b32_e32 v86, v2
	v_mov_b32_e32 v87, v2
	v_mov_b32_e32 v88, v2
	v_mov_b32_e32 v89, v2
	v_mov_b32_e32 v94, v2
	v_mov_b32_e32 v95, v2
	v_mov_b32_e32 v96, v2
	v_mov_b32_e32 v97, v2
	v_mov_b32_e32 v102, v2
	v_mov_b32_e32 v103, v2
	v_mov_b32_e32 v104, v2
	v_mov_b32_e32 v105, v2
	v_mov_b32_e32 v110, v2
	v_mov_b32_e32 v111, v2
	v_mov_b32_e32 v112, v2
	v_mov_b32_e32 v113, v2
	v_mov_b32_e32 v118, v2
	v_mov_b32_e32 v119, v2
	v_mov_b32_e32 v120, v2
	v_mov_b32_e32 v121, v2
	v_mov_b32_e32 v126, v2
	v_mov_b32_e32 v127, v2
	v_mov_b32_e32 v128, v2
	v_mov_b32_e32 v129, v2
	.p2align	6

; template <class Epi, class Sched, bool ALIGN_EPI = false, bool SP2 = false, bool SPLITK = false>
; __device__ __forceinline__ void gemm_phase(PG8_LAS unsigned char* lds, const Gemm g, const Sched& S, const Epi& E) {
;     ...
; #pragma unroll
;         for (int a = 0; a < 2; ++a)
; #pragma unroll
;             for (int b = 0; b < 2; ++b)
; #pragma unroll
;                 for (int m = 0; m < 4; ++m)
; #pragma unroll
;                     for (int n = 0; n < 2; ++n) acc[a][b][m][n] = (f32x4){0.f, 0.f, 0.f, 0.f};
.LBB0_700:
	s_add_u32 s12, s46, 0x100
	v_mov_b32_e32 v2, 0
	s_addc_u32 s45, s47, 0
	s_mov_b32 s57, -2
	v_mov_b32_e32 v3, v2
	v_mov_b32_e32 v4, v2
	v_mov_b32_e32 v5, v2
	v_mov_b32_e32 v6, v2
	v_mov_b32_e32 v7, v2
	v_mov_b32_e32 v8, v2
	v_mov_b32_e32 v9, v2
	v_mov_b32_e32 v18, v2
	v_mov_b32_e32 v19, v2
	v_mov_b32_e32 v20, v2
	v_mov_b32_e32 v21, v2
	v_mov_b32_e32 v22, v2
	v_mov_b32_e32 v23, v2
	v_mov_b32_e32 v24, v2
	v_mov_b32_e32 v25, v2
	v_mov_b32_e32 v34, v2
	v_mov_b32_e32 v35, v2
	v_mov_b32_e32 v36, v2
	v_mov_b32_e32 v37, v2
	v_mov_b32_e32 v38, v2
	v_mov_b32_e32 v39, v2
	v_mov_b32_e32 v40, v2
	v_mov_b32_e32 v41, v2
	v_mov_b32_e32 v50, v2
	v_mov_b32_e32 v51, v2
	v_mov_b32_e32 v52, v2
	v_mov_b32_e32 v53, v2
	v_mov_b32_e32 v54, v2
	v_mov_b32_e32 v55, v2
	v_mov_b32_e32 v56, v2
	v_mov_b32_e32 v57, v2
	v_mov_b32_e32 v10, v2
	v_mov_b32_e32 v11, v2
	v_mov_b32_e32 v12, v2
	v_mov_b32_e32 v13, v2
	v_mov_b32_e32 v14, v2
	v_mov_b32_e32 v15, v2
	v_mov_b32_e32 v16, v2
	v_mov_b32_e32 v17, v2
	v_mov_b32_e32 v26, v2
	v_mov_b32_e32 v27, v2
	v_mov_b32_e32 v28, v2
	v_mov_b32_e32 v29, v2
	v_mov_b32_e32 v30, v2
	v_mov_b32_e32 v31, v2
	v_mov_b32_e32 v32, v2
	v_mov_b32_e32 v33, v2
	v_mov_b32_e32 v42, v2
	v_mov_b32_e32 v43, v2
	v_mov_b32_e32 v44, v2
	v_mov_b32_e32 v45, v2
	v_mov_b32_e32 v46, v2
	v_mov_b32_e32 v47, v2
	v_mov_b32_e32 v48, v2
	v_mov_b32_e32 v49, v2
	v_mov_b32_e32 v58, v2
	v_mov_b32_e32 v59, v2
	v_mov_b32_e32 v60, v2
	v_mov_b32_e32 v61, v2
	v_mov_b32_e32 v62, v2
	v_mov_b32_e32 v63, v2
	v_mov_b32_e32 v64, v2
	v_mov_b32_e32 v65, v2
	v_mov_b32_e32 v66, v2
	v_mov_b32_e32 v67, v2
	v_mov_b32_e32 v68, v2
	v_mov_b32_e32 v69, v2
	v_mov_b32_e32 v70, v2
	v_mov_b32_e32 v71, v2
	v_mov_b32_e32 v72, v2
	v_mov_b32_e32 v73, v2
	v_mov_b32_e32 v86, v2
	v_mov_b32_e32 v87, v2
	v_mov_b32_e32 v88, v2
	v_mov_b32_e32 v89, v2
	v_mov_b32_e32 v90, v2
	v_mov_b32_e32 v91, v2
	v_mov_b32_e32 v92, v2
	v_mov_b32_e32 v93, v2
	v_mov_b32_e32 v110, v2
	v_mov_b32_e32 v111, v2
	v_mov_b32_e32 v112, v2
	v_mov_b32_e32 v113, v2
	v_mov_b32_e32 v114, v2
	v_mov_b32_e32 v115, v2
	v_mov_b32_e32 v116, v2
	v_mov_b32_e32 v117, v2
	v_mov_b32_e32 v134, v2
	v_mov_b32_e32 v135, v2
	v_mov_b32_e32 v136, v2
	v_mov_b32_e32 v137, v2
	v_mov_b32_e32 v138, v2
	v_mov_b32_e32 v139, v2
	v_mov_b32_e32 v140, v2
	v_mov_b32_e32 v141, v2
	v_mov_b32_e32 v74, v2
	v_mov_b32_e32 v75, v2
	v_mov_b32_e32 v76, v2
	v_mov_b32_e32 v77, v2
	v_mov_b32_e32 v78, v2
	v_mov_b32_e32 v79, v2
	v_mov_b32_e32 v80, v2
	v_mov_b32_e32 v81, v2
	v_mov_b32_e32 v98, v2
	v_mov_b32_e32 v99, v2
	v_mov_b32_e32 v100, v2
	v_mov_b32_e32 v101, v2
	v_mov_b32_e32 v102, v2
	v_mov_b32_e32 v103, v2
	v_mov_b32_e32 v104, v2
	v_mov_b32_e32 v105, v2
	v_mov_b32_e32 v122, v2
	v_mov_b32_e32 v123, v2
	v_mov_b32_e32 v124, v2
	v_mov_b32_e32 v125, v2
	v_mov_b32_e32 v126, v2
	v_mov_b32_e32 v127, v2
	v_mov_b32_e32 v128, v2
	v_mov_b32_e32 v129, v2
	v_mov_b32_e32 v154, v2
	v_mov_b32_e32 v155, v2
	v_mov_b32_e32 v156, v2
	v_mov_b32_e32 v157, v2
	v_mov_b32_e32 v158, v2
	v_mov_b32_e32 v159, v2
	v_mov_b32_e32 v160, v2
	v_mov_b32_e32 v161, v2
	.p2align	6
